# conversion work-list rebalancing: 2816 gate/up items of each MLA layer move from its w_in phase (conversion-critical) to the previous layer's gate/up-phase idle tail (slack); on v058 stack
# baseline (speedup 1.0000x reference)
.LBB0_299:
	s_abs_i32 s6, s80
	v_cvt_f32_u32_e32 v0, s6
	s_sub_i32 s7, 0, s6
	v_rcp_iflag_f32_e32 v0, v0
	s_nop 0
	v_mul_f32_e32 v0, 0x4f7ffffe, v0
	v_cvt_u32_f32_e32 v0, v0
	s_nop 0
	v_readfirstlane_b32 s8, v0
	s_mul_i32 s7, s7, s8
	s_mul_hi_u32 s7, s8, s7
	s_add_i32 s8, s8, s7
	s_mul_hi_u32 s7, s8, 0xa0
	s_mul_i32 s7, s7, s6
	s_sub_i32 s7, 0xa0, s7
	s_sub_i32 s8, s7, s6
	s_cmp_ge_u32 s7, s6
	s_cselect_b32 s7, s8, s7
	s_sub_i32 s8, s7, s6
	s_cmp_ge_u32 s7, s6
	s_cselect_b32 s6, s8, s7
	s_cmp_lt_i32 s81, s6
	s_cbranch_scc1 .LBB0_360
	s_ashr_i32 s7, s82, 6
	s_mul_i32 s8, s76, 0xab40
	s_sub_i32 s9, s81, s6
	s_add_i32 s18, s8, 0x9540
	s_lshl_b32 s9, s9, 3
	s_add_i32 s8, s8, s7
	s_add_i32 s8, s8, s9
	s_add_i32 s19, s8, 0x7440
	s_cmp_ge_i32 s19, s18
	s_cbranch_scc1 .LBB0_360
	s_sub_i32 s6, s80, s6
	s_lshl_b32 s20, s6, 3
	s_lshl_b32 s6, s7, 14
	s_add_i32 s6, s6, 0
	s_add_u32 s21, s10, 0x10612000
	s_addc_u32 s22, s11, 0
	s_add_u32 s23, s10, 0x5612000
	s_addc_u32 s24, s11, 0
	s_add_u32 s25, s10, 0x4612000
	s_addc_u32 s26, s11, 0
	s_add_u32 s27, s10, 0x3e12000
	s_addc_u32 s28, s11, 0
	s_add_u32 s29, s10, 0x3812000
	s_addc_u32 s30, s11, 0
	s_add_u32 s31, s10, 0x1e12000
	v_bfe_u32 v10, v188, 3, 3
	s_addc_u32 s33, s11, 0
	v_lshlrev_b32_e32 v0, 2, v188
	v_and_b32_e32 v3, 7, v188
	v_lshlrev_b32_e32 v6, 2, v10
	s_add_u32 s34, s10, 0x612000
	v_and_b32_e32 v0, 28, v0
	v_lshl_add_u32 v4, v3, 4, s6
	v_mul_u32_u24_e32 v5, 0x84, v10
	v_lshlrev_b32_e32 v2, 3, v3
	v_mul_u32_u24_e32 v3, 0x420, v3
	v_and_b32_e32 v14, 16, v6
	s_addc_u32 s35, s11, 0
	v_or_b32_e32 v11, 8, v10
	v_or_b32_e32 v12, 16, v10
	v_or_b32_e32 v13, 24, v10
	v_add3_u32 v15, s6, v3, v6
	v_or_b32_e32 v16, 4, v14
	v_or_b32_e32 v17, 8, v14
	v_or_b32_e32 v18, 12, v6
	v_lshlrev_b32_e32 v0, 2, v0
	v_add_u32_e32 v19, v4, v5
	v_lshlrev_b32_e32 v6, 1, v2
	s_mov_b32 s99, 0
	s_branch .LBB0_304

.LBB0_1067:
	s_abs_i32 s4, s36
	v_cvt_f32_u32_e32 v0, s4
	s_sub_i32 s5, 0, s4
	v_rcp_iflag_f32_e32 v0, v0
	s_nop 0
	v_mul_f32_e32 v0, 0x4f7ffffe, v0
	v_cvt_u32_f32_e32 v0, v0
	s_nop 0
	v_readfirstlane_b32 s8, v0
	s_mul_i32 s5, s5, s8
	s_mul_hi_u32 s5, s8, s5
	s_add_i32 s8, s8, s5
	s_mul_hi_u32 s5, s8, 0x580
	s_mul_i32 s5, s5, s4
	s_sub_i32 s5, 0x580, s5
	s_sub_i32 s8, s5, s4
	s_cmp_ge_u32 s5, s4
	s_cselect_b32 s5, s8, s5
	s_sub_i32 s8, s5, s4
	s_cmp_ge_u32 s5, s4
	s_cselect_b32 s4, s8, s5
	s_cmp_lt_i32 s37, s4
	s_cbranch_scc1 .LBB0_1128
	s_ashr_i32 s5, s38, 6
	s_and_b64 s[8:9], s[74:75], exec
	s_waitcnt lgkmcnt(0)
	s_cselect_b32 s11, s90, 0x1340
	s_add_i32 s8, s56, 1
	s_lshr_b32 s9, s8, 1
	s_bitcmp1_b32 s8, 0
	s_mul_i32 s9, s9, 0xab40
	s_cselect_b32 s8, 0x5600, 0
	s_add_i32 s14, s9, s8
	s_and_b64 s[8:9], s[74:75], exec
	s_cselect_b32 s8, 0x1e40, s90
	s_add_i32 s14, s14, s8
	s_cmp_eq_u32 s57, 1
	s_mov_b32 s8, 0x8200
	s_mul_i32 s10, s76, 0xab40
	s_cselect_b32 s8, s8, 0x2c00
	s_add_i32 s8, s8, s10
	s_add_i32 s8, s8, s11
	s_add_i32 s8, s8, s5
	s_cmp_lg_u32 s56, 3
	s_cselect_b32 s16, s14, 0x15680
	s_sub_i32 s9, s37, s4
	s_lshl_b32 s9, s9, 3
	s_add_i32 s17, s8, s9
	s_cmp_ge_i32 s17, s16
	s_cbranch_scc1 .LBB0_1128
	s_sub_i32 s4, s36, s4
	s_lshl_b32 s18, s4, 3
	s_lshl_b32 s4, s5, 14
	s_add_i32 s4, s4, 0
	s_add_u32 s19, s6, 0x10612000
	s_addc_u32 s20, s7, 0
	s_add_u32 s21, s6, 0x4612000
	s_addc_u32 s22, s7, 0
	s_add_u32 s23, s6, 0x3e12000
	s_addc_u32 s24, s7, 0
	s_add_u32 s25, s6, 0x3812000
	s_addc_u32 s26, s7, 0
	s_add_u32 s27, s6, 0x2e12000
	s_addc_u32 s28, s7, 0
	s_add_u32 s29, s6, 0x1e12000
	v_bfe_u32 v10, v136, 3, 3
	s_addc_u32 s30, s7, 0
	v_lshlrev_b32_e32 v0, 2, v136
	v_and_b32_e32 v3, 7, v136
	v_lshlrev_b32_e32 v6, 2, v10
	s_add_u32 s31, s6, 0x612000
	v_and_b32_e32 v0, 28, v0
	v_lshl_add_u32 v4, v3, 4, s4
	v_mul_u32_u24_e32 v5, 0x84, v10
	v_lshlrev_b32_e32 v2, 3, v3
	v_mul_u32_u24_e32 v3, 0x420, v3
	v_and_b32_e32 v14, 16, v6
	s_addc_u32 s33, s7, 0
	v_or_b32_e32 v11, 8, v10
	v_or_b32_e32 v12, 16, v10
	v_or_b32_e32 v13, 24, v10
	v_add3_u32 v15, s4, v3, v6
	v_or_b32_e32 v16, 4, v14
	v_or_b32_e32 v17, 8, v14
	v_or_b32_e32 v18, 12, v6
	v_lshlrev_b32_e32 v0, 2, v0
	v_add_u32_e32 v19, v4, v5
	v_lshlrev_b32_e32 v6, 1, v2
	s_mov_b32 s99, 0
	s_branch .LBB0_1072
